# v81 + P9 K-loops: redundant post-barrier lgkmcnt wait removed (priority flips kept), bursts at phase 4
# baseline (speedup 1.0000x reference)
; #define PG8_STAGE(bufoff, gbase, voff) do { _Pragma("unroll") for (int _i = 0; _i < 2; ++_i) \
;         __builtin_amdgcn_global_load_lds((const unsigned*)((const char*)(gbase) + (voff)[_i]), (PG8_LAS unsigned*)(lds + (bufoff) + ldsw + _i * 8192), 16, 0, 0); } while (0)
; #define PG8_STAGE_NT(bufoff, gbase, voff) do { _Pragma("unroll") for (int _i = 0; _i < 2; ++_i) \
;         __builtin_amdgcn_global_load_lds((const unsigned*)((const char*)(gbase) + (voff)[_i]), (PG8_LAS unsigned*)(lds + (bufoff) + ldsw + _i * 8192), 16, 0, PG8_B_AUX); } while (0)
; #define PG8_LDA(dst, b, h) do { _Pragma("unroll") for (int m = 0; m < 4; ++m) _Pragma("unroll") for (int k = 0; k < 2; ++k) dst[m][k] = *(const PG8_LAS bf16x8*)(lds + PG8_SA(b, h) + aoff + m * 2048 + k * 1024); } while (0)
; #define PG8_LDB(dst, b, h) do { _Pragma("unroll") for (int n = 0; n < 2; ++n) _Pragma("unroll") for (int k = 0; k < 2; ++k) dst[n][k] = *(const PG8_LAS bf16x8*)(lds + PG8_SB(b, h) + boff + n * 2048 + k * 1024); } while (0)
; #define PG8_WAIT_V(n) asm volatile("s_waitcnt vmcnt(" #n ")" ::: "memory")
; #define PG8_WAIT_L(n) asm volatile("s_waitcnt lgkmcnt(" #n ")" ::: "memory")
; #define PG8_BAR __builtin_amdgcn_s_barrier()
; #define PG8_SCHED __builtin_amdgcn_sched_barrier(0)
; template <class Epi, class Sched, bool ALIGN_EPI = false, bool SP2 = false>
; __device__ __forceinline__ void gemm_phase(PG8_LAS unsigned char* lds, const Gemm g, const Sched& S, const Epi& E, int wid) {
;     ...
;             const bool last = (t == nt - 2);
;             const char* a1 = cA + (size_t)(t + 1) * kstep;
;             const char* a2 = last ? nA : cA + (size_t)(t + 2) * kstep; const char* b2 = last ? nB : cB + (size_t)(t + 2) * kstep;
;             const char* a3 = a2 + kstep; const char* b3 = b2 + kstep;
;             if (last && has_next) S.a_ready(nxt);
;             if constexpr (SP2) {
;             PG8_LDB(B0, 0, 0); PG8_LDB(B1, 0, 1); PG8_SCHED; PG8_LDA(At, 0, 0); PG8_STAGE(PG8_SA(1, 1), a1 + hstepA, voffA);
;             PG8_WAIT_V(8); PG8_WAIT_L(0); PG8_BAR; PG8_MMA(0, 0, At, B0); PG8_MMA(0, 1, At, B1); PG8_BAR; PG8_SCHED;
;             PG8_LDA(At, 0, 1); PG8_STAGE_NT(PG8_SB(0, 0), b2, voffB); PG8_STAGE_NT(PG8_SB(0, 1), b2 + hstepB, voffB); PG8_STAGE(PG8_SA(0, 0), a2, voffA);
;             PG8_WAIT_V(8); PG8_WAIT_L(0); PG8_BAR; PG8_MMA(1, 0, At, B0); PG8_MMA(1, 1, At, B1); PG8_BAR; PG8_SCHED;
.LBB0_1221:
	ds_read_b128 v[128:131], v205
	ds_read_b128 v[132:135], v205 offset:1024
	ds_read_b128 v[136:139], v205 offset:2048
	ds_read_b128 v[140:143], v205 offset:3072
	ds_read_b128 v[144:147], v206
	ds_read_b128 v[148:151], v206 offset:1024
	ds_read_b128 v[152:155], v206 offset:2048
	ds_read_b128 v[156:159], v206 offset:3072
	s_add_u32 s48, s46, 0x100
	s_addc_u32 s49, s47, 0
	s_cmpk_eq_i32 s63, 0xa8
	s_cselect_b32 s53, s7, s49
	s_cselect_b32 s52, s6, s48
	s_cselect_b32 s51, s45, s62
	s_cselect_b32 s50, s44, s61
	v_lshl_add_u64 v[200:201], s[46:47], 0, v[176:177]
	s_add_i32 m0, s17, 0xc000
	ds_read_b128 v[160:163], v207
	ds_read_b128 v[164:167], v207 offset:1024
	ds_read_b128 v[184:187], v207 offset:2048
	ds_read_b128 v[188:191], v207 offset:3072
	ds_read_b128 v[192:195], v207 offset:4096
	ds_read_b128 v[196:199], v207 offset:5120
	ds_read_b128 v[210:213], v207 offset:6144
	ds_read_b128 v[214:217], v207 offset:7168
	global_load_lds_dwordx4 v[200:201], off
	v_lshl_add_u64 v[200:201], s[46:47], 0, v[178:179]
	s_add_i32 m0, s17, 0xe000
	s_nop 0
	global_load_lds_dwordx4 v[200:201], off
	s_nop 0
	s_waitcnt vmcnt(8)
	s_waitcnt lgkmcnt(0)
	s_barrier
	s_setprio 1
	v_mfma_f32_16x16x32_bf16 v[124:127], v[128:131], v[160:163], v[124:127]
	v_mfma_f32_16x16x32_bf16 v[120:123], v[136:139], v[160:163], v[120:123]
	v_mfma_f32_16x16x32_bf16 v[116:119], v[128:131], v[184:187], v[116:119]
	v_mfma_f32_16x16x32_bf16 v[112:115], v[136:139], v[184:187], v[112:115]
	v_mfma_f32_16x16x32_bf16 v[92:95], v[128:131], v[192:195], v[92:95]
	v_mfma_f32_16x16x32_bf16 v[88:91], v[136:139], v[192:195], v[88:91]
	v_mfma_f32_16x16x32_bf16 v[76:79], v[128:131], v[210:213], v[76:79]
	v_mfma_f32_16x16x32_bf16 v[72:75], v[136:139], v[210:213], v[72:75]
	v_mfma_f32_16x16x32_bf16 v[124:127], v[132:135], v[164:167], v[124:127]
	v_mfma_f32_16x16x32_bf16 v[120:123], v[140:143], v[164:167], v[120:123]
	v_mfma_f32_16x16x32_bf16 v[116:119], v[132:135], v[188:191], v[116:119]
	v_mfma_f32_16x16x32_bf16 v[112:115], v[140:143], v[188:191], v[112:115]
	v_mfma_f32_16x16x32_bf16 v[92:95], v[132:135], v[196:199], v[92:95]
	v_mfma_f32_16x16x32_bf16 v[88:91], v[140:143], v[196:199], v[88:91]
	v_mfma_f32_16x16x32_bf16 v[76:79], v[132:135], v[214:217], v[76:79]
	v_mfma_f32_16x16x32_bf16 v[72:75], v[140:143], v[214:217], v[72:75]
	s_setprio 0
	s_setprio 1
	v_mfma_f32_16x16x32_bf16 v[108:111], v[144:147], v[160:163], v[108:111]
	v_mfma_f32_16x16x32_bf16 v[104:107], v[152:155], v[160:163], v[104:107]
	v_mfma_f32_16x16x32_bf16 v[100:103], v[144:147], v[184:187], v[100:103]
	v_mfma_f32_16x16x32_bf16 v[96:99], v[152:155], v[184:187], v[96:99]
	v_mfma_f32_16x16x32_bf16 v[84:87], v[144:147], v[192:195], v[84:87]
	v_mfma_f32_16x16x32_bf16 v[80:83], v[152:155], v[192:195], v[80:83]
	v_mfma_f32_16x16x32_bf16 v[68:71], v[144:147], v[210:213], v[68:71]
	v_mfma_f32_16x16x32_bf16 v[64:67], v[152:155], v[210:213], v[64:67]
	v_mfma_f32_16x16x32_bf16 v[108:111], v[148:151], v[164:167], v[108:111]
	v_mfma_f32_16x16x32_bf16 v[104:107], v[156:159], v[164:167], v[104:107]
	v_mfma_f32_16x16x32_bf16 v[100:103], v[148:151], v[188:191], v[100:103]
	v_mfma_f32_16x16x32_bf16 v[96:99], v[156:159], v[188:191], v[96:99]
	v_mfma_f32_16x16x32_bf16 v[84:87], v[148:151], v[196:199], v[84:87]
	v_mfma_f32_16x16x32_bf16 v[80:83], v[156:159], v[196:199], v[80:83]
	v_mfma_f32_16x16x32_bf16 v[68:71], v[148:151], v[214:217], v[68:71]
	v_mfma_f32_16x16x32_bf16 v[64:67], v[156:159], v[214:217], v[64:67]
	s_setprio 0
	s_barrier
	s_add_i32 s46, s56, s9
	v_lshl_add_u64 v[200:201], s[50:51], 0, v[170:171]
	s_mov_b32 m0, s46
	ds_read_b128 v[160:163], v207 offset:16384
	ds_read_b128 v[164:167], v207 offset:17408
	ds_read_b128 v[184:187], v207 offset:18432
	ds_read_b128 v[188:191], v207 offset:19456
	ds_read_b128 v[192:195], v207 offset:20480
	ds_read_b128 v[196:199], v207 offset:21504
	ds_read_b128 v[210:213], v207 offset:22528
	ds_read_b128 v[214:217], v207 offset:23552
	global_load_lds_dwordx4 v[200:201], off
	s_add_i32 m0, s46, 0x2000
	s_add_u32 s46, s50, 0x2b4000
	v_lshl_add_u64 v[218:219], s[50:51], 0, v[174:175]
	s_addc_u32 s47, s51, 0
	s_add_i32 s64, s57, s9
	global_load_lds_dwordx4 v[218:219], off
	v_lshl_add_u64 v[220:221], s[46:47], 0, v[170:171]
	s_mov_b32 m0, s64
	v_lshl_add_u64 v[222:223], s[52:53], 0, v[172:173]
	global_load_lds_dwordx4 v[220:221], off
	v_lshl_add_u64 v[220:221], s[46:47], 0, v[174:175]
	s_add_i32 m0, s64, 0x2000
	s_nop 0
	global_load_lds_dwordx4 v[220:221], off
	v_lshl_add_u64 v[220:221], s[52:53], 0, v[168:169]
	s_mov_b32 m0, s17
	s_nop 0
	global_load_lds_dwordx4 v[220:221], off
	s_mov_b32 m0, s19
	s_nop 0
	global_load_lds_dwordx4 v[222:223], off
	s_waitcnt vmcnt(8)
	s_waitcnt lgkmcnt(0)
	s_barrier
; #define PG8_STAGE(bufoff, gbase, voff) do { _Pragma("unroll") for (int _i = 0; _i < 2; ++_i) \
;         __builtin_amdgcn_global_load_lds((const unsigned*)((const char*)(gbase) + (voff)[_i]), (PG8_LAS unsigned*)(lds + (bufoff) + ldsw + _i * 8192), 16, 0, 0); } while (0)
; #define PG8_STAGE_NT(bufoff, gbase, voff) do { _Pragma("unroll") for (int _i = 0; _i < 2; ++_i) \
;         __builtin_amdgcn_global_load_lds((const unsigned*)((const char*)(gbase) + (voff)[_i]), (PG8_LAS unsigned*)(lds + (bufoff) + ldsw + _i * 8192), 16, 0, PG8_B_AUX); } while (0)
; #define PG8_LDA(dst, b, h) do { _Pragma("unroll") for (int m = 0; m < 4; ++m) _Pragma("unroll") for (int k = 0; k < 2; ++k) dst[m][k] = *(const PG8_LAS bf16x8*)(lds + PG8_SA(b, h) + aoff + m * 2048 + k * 1024); } while (0)
; #define PG8_LDB(dst, b, h) do { _Pragma("unroll") for (int n = 0; n < 2; ++n) _Pragma("unroll") for (int k = 0; k < 2; ++k) dst[n][k] = *(const PG8_LAS bf16x8*)(lds + PG8_SB(b, h) + boff + n * 2048 + k * 1024); } while (0)
; #define PG8_WAIT_V(n) asm volatile("s_waitcnt vmcnt(" #n ")" ::: "memory")
; #define PG8_BAR __builtin_amdgcn_s_barrier()
; template <class Epi, class Sched, bool ALIGN_EPI = false, bool SP2 = false>
; __device__ __forceinline__ void gemm_phase(PG8_LAS unsigned char* lds, const Gemm g, const Sched& S, const Epi& E, int wid) {
;     ...
;             PG8_LDB(B0, 0, 0); PG8_LDB(B1, 0, 1); PG8_SCHED; PG8_LDA(At, 0, 0); PG8_STAGE(PG8_SA(1, 1), a1 + hstepA, voffA);
;             PG8_WAIT_V(8); PG8_WAIT_L(0); PG8_BAR; PG8_MMA(0, 0, At, B0); PG8_MMA(0, 1, At, B1); PG8_BAR; PG8_SCHED;
;             PG8_LDA(At, 0, 1); PG8_STAGE_NT(PG8_SB(0, 0), b2, voffB); PG8_STAGE_NT(PG8_SB(0, 1), b2 + hstepB, voffB); PG8_STAGE(PG8_SA(0, 0), a2, voffA);
;             PG8_WAIT_V(8); PG8_WAIT_L(0); PG8_BAR; PG8_MMA(1, 0, At, B0); PG8_MMA(1, 1, At, B1); PG8_BAR; PG8_SCHED;
;             PG8_LDB(B0, 1, 0); PG8_LDB(B1, 1, 1); PG8_SCHED; PG8_LDA(At, 1, 0); PG8_STAGE(PG8_SA(0, 1), a2 + hstepA, voffA);
;             PG8_WAIT_V(8); PG8_WAIT_L(0); PG8_BAR; PG8_MMA(0, 0, At, B0); PG8_MMA(0, 1, At, B1); PG8_BAR; PG8_SCHED;
;             PG8_LDA(At, 1, 1); PG8_STAGE_NT(PG8_SB(1, 0), b3, voffB); PG8_STAGE_NT(PG8_SB(1, 1), b3 + hstepB, voffB); PG8_STAGE(PG8_SA(1, 0), a3, voffA);
;             PG8_WAIT_V(8); PG8_WAIT_L(0); PG8_BAR; PG8_MMA(1, 0, At, B0); PG8_MMA(1, 1, At, B1); PG8_BAR; PG8_SCHED;
	s_setprio 1
	v_mfma_f32_16x16x32_bf16 v[60:63], v[128:131], v[160:163], v[60:63]
	v_mfma_f32_16x16x32_bf16 v[56:59], v[136:139], v[160:163], v[56:59]
	v_mfma_f32_16x16x32_bf16 v[44:47], v[128:131], v[184:187], v[44:47]
	v_mfma_f32_16x16x32_bf16 v[40:43], v[136:139], v[184:187], v[40:43]
	v_mfma_f32_16x16x32_bf16 v[28:31], v[128:131], v[192:195], v[28:31]
	v_mfma_f32_16x16x32_bf16 v[24:27], v[136:139], v[192:195], v[24:27]
	v_mfma_f32_16x16x32_bf16 v[12:15], v[128:131], v[210:213], v[12:15]
	v_mfma_f32_16x16x32_bf16 v[8:11], v[136:139], v[210:213], v[8:11]
	v_mfma_f32_16x16x32_bf16 v[60:63], v[132:135], v[164:167], v[60:63]
	v_mfma_f32_16x16x32_bf16 v[56:59], v[140:143], v[164:167], v[56:59]
	v_mfma_f32_16x16x32_bf16 v[44:47], v[132:135], v[188:191], v[44:47]
	v_mfma_f32_16x16x32_bf16 v[40:43], v[140:143], v[188:191], v[40:43]
	v_mfma_f32_16x16x32_bf16 v[28:31], v[132:135], v[196:199], v[28:31]
	v_mfma_f32_16x16x32_bf16 v[24:27], v[140:143], v[196:199], v[24:27]
	v_mfma_f32_16x16x32_bf16 v[12:15], v[132:135], v[214:217], v[12:15]
	v_mfma_f32_16x16x32_bf16 v[8:11], v[140:143], v[214:217], v[8:11]
	s_setprio 0
	s_setprio 1
	v_mfma_f32_16x16x32_bf16 v[52:55], v[144:147], v[160:163], v[52:55]
	v_mfma_f32_16x16x32_bf16 v[48:51], v[152:155], v[160:163], v[48:51]
	v_mfma_f32_16x16x32_bf16 v[36:39], v[144:147], v[184:187], v[36:39]
	v_mfma_f32_16x16x32_bf16 v[32:35], v[152:155], v[184:187], v[32:35]
	v_mfma_f32_16x16x32_bf16 v[20:23], v[144:147], v[192:195], v[20:23]
	v_mfma_f32_16x16x32_bf16 v[16:19], v[152:155], v[192:195], v[16:19]
	v_mfma_f32_16x16x32_bf16 v[4:7], v[144:147], v[210:213], v[4:7]
	v_mfma_f32_16x16x32_bf16 v[0:3], v[152:155], v[210:213], v[0:3]
	v_mfma_f32_16x16x32_bf16 v[52:55], v[148:151], v[164:167], v[52:55]
	v_mfma_f32_16x16x32_bf16 v[48:51], v[156:159], v[164:167], v[48:51]
	v_mfma_f32_16x16x32_bf16 v[36:39], v[148:151], v[188:191], v[36:39]
	v_mfma_f32_16x16x32_bf16 v[32:35], v[156:159], v[188:191], v[32:35]
	v_mfma_f32_16x16x32_bf16 v[20:23], v[148:151], v[196:199], v[20:23]
	v_mfma_f32_16x16x32_bf16 v[16:19], v[156:159], v[196:199], v[16:19]
	v_mfma_f32_16x16x32_bf16 v[4:7], v[148:151], v[214:217], v[4:7]
	v_mfma_f32_16x16x32_bf16 v[0:3], v[156:159], v[214:217], v[0:3]
	s_setprio 0
	s_barrier
	s_add_i32 s64, 0, 0x18000
	s_add_i32 s65, 0, 0x1c000
	v_add_u32_e32 v140, s64, v203
	v_add_u32_e32 v156, s65, v203
	ds_read_b128 v[128:131], v140
	ds_read_b128 v[132:135], v140 offset:1024
	ds_read_b128 v[136:139], v140 offset:2048
	ds_read_b128 v[140:143], v140 offset:3072
	ds_read_b128 v[144:147], v156
	ds_read_b128 v[148:151], v156 offset:1024
	ds_read_b128 v[152:155], v156 offset:2048
	ds_read_b128 v[156:159], v156 offset:3072
	s_add_u32 s46, s52, 0x2b4000
	s_addc_u32 s47, s53, 0
	s_mov_b32 m0, s22
	v_lshl_add_u64 v[224:225], s[46:47], 0, v[168:169]
	ds_read_b128 v[160:163], v207 offset:32768
	ds_read_b128 v[164:167], v207 offset:33792
	ds_read_b128 v[184:187], v207 offset:34816
	ds_read_b128 v[188:191], v207 offset:35840
	ds_read_b128 v[192:195], v207 offset:36864
	ds_read_b128 v[196:199], v207 offset:37888
	ds_read_b128 v[210:213], v207 offset:38912
	ds_read_b128 v[214:217], v207 offset:39936
	global_load_lds_dwordx4 v[224:225], off
	v_lshl_add_u64 v[224:225], s[46:47], 0, v[172:173]
	s_mov_b32 m0, s23
	s_nop 0
	global_load_lds_dwordx4 v[224:225], off
	s_waitcnt vmcnt(8)
	s_waitcnt lgkmcnt(0)
	s_barrier
	s_setprio 1
	v_mfma_f32_16x16x32_bf16 v[124:127], v[128:131], v[160:163], v[124:127]
	v_mfma_f32_16x16x32_bf16 v[120:123], v[136:139], v[160:163], v[120:123]
	v_mfma_f32_16x16x32_bf16 v[116:119], v[128:131], v[184:187], v[116:119]
	v_mfma_f32_16x16x32_bf16 v[112:115], v[136:139], v[184:187], v[112:115]
	v_mfma_f32_16x16x32_bf16 v[92:95], v[128:131], v[192:195], v[92:95]
	v_mfma_f32_16x16x32_bf16 v[88:91], v[136:139], v[192:195], v[88:91]
	v_mfma_f32_16x16x32_bf16 v[76:79], v[128:131], v[210:213], v[76:79]
	v_mfma_f32_16x16x32_bf16 v[72:75], v[136:139], v[210:213], v[72:75]
	v_mfma_f32_16x16x32_bf16 v[124:127], v[132:135], v[164:167], v[124:127]
	v_mfma_f32_16x16x32_bf16 v[120:123], v[140:143], v[164:167], v[120:123]
	v_mfma_f32_16x16x32_bf16 v[116:119], v[132:135], v[188:191], v[116:119]
	v_mfma_f32_16x16x32_bf16 v[112:115], v[140:143], v[188:191], v[112:115]
	v_mfma_f32_16x16x32_bf16 v[92:95], v[132:135], v[196:199], v[92:95]
	v_mfma_f32_16x16x32_bf16 v[88:91], v[140:143], v[196:199], v[88:91]
	v_mfma_f32_16x16x32_bf16 v[76:79], v[132:135], v[214:217], v[76:79]
	v_mfma_f32_16x16x32_bf16 v[72:75], v[140:143], v[214:217], v[72:75]
	s_setprio 0
	s_setprio 1
	v_mfma_f32_16x16x32_bf16 v[108:111], v[144:147], v[160:163], v[108:111]
	v_mfma_f32_16x16x32_bf16 v[104:107], v[152:155], v[160:163], v[104:107]
	v_mfma_f32_16x16x32_bf16 v[100:103], v[144:147], v[184:187], v[100:103]
	v_mfma_f32_16x16x32_bf16 v[96:99], v[152:155], v[184:187], v[96:99]
	v_mfma_f32_16x16x32_bf16 v[84:87], v[144:147], v[192:195], v[84:87]
	v_mfma_f32_16x16x32_bf16 v[80:83], v[152:155], v[192:195], v[80:83]
	v_mfma_f32_16x16x32_bf16 v[68:71], v[144:147], v[210:213], v[68:71]
	v_mfma_f32_16x16x32_bf16 v[64:67], v[152:155], v[210:213], v[64:67]
	v_mfma_f32_16x16x32_bf16 v[108:111], v[148:151], v[164:167], v[108:111]
	v_mfma_f32_16x16x32_bf16 v[104:107], v[156:159], v[164:167], v[104:107]
	v_mfma_f32_16x16x32_bf16 v[100:103], v[148:151], v[188:191], v[100:103]
	v_mfma_f32_16x16x32_bf16 v[96:99], v[156:159], v[188:191], v[96:99]
	v_mfma_f32_16x16x32_bf16 v[84:87], v[148:151], v[196:199], v[84:87]
	v_mfma_f32_16x16x32_bf16 v[80:83], v[156:159], v[196:199], v[80:83]
	v_mfma_f32_16x16x32_bf16 v[68:71], v[148:151], v[214:217], v[68:71]
	v_mfma_f32_16x16x32_bf16 v[64:67], v[156:159], v[214:217], v[64:67]
	s_setprio 0
	s_barrier
; #define PG8_STAGE(bufoff, gbase, voff) do { _Pragma("unroll") for (int _i = 0; _i < 2; ++_i) \
;         __builtin_amdgcn_global_load_lds((const unsigned*)((const char*)(gbase) + (voff)[_i]), (PG8_LAS unsigned*)(lds + (bufoff) + ldsw + _i * 8192), 16, 0, 0); } while (0)
; #define PG8_STAGE_NT(bufoff, gbase, voff) do { _Pragma("unroll") for (int _i = 0; _i < 2; ++_i) \
;         __builtin_amdgcn_global_load_lds((const unsigned*)((const char*)(gbase) + (voff)[_i]), (PG8_LAS unsigned*)(lds + (bufoff) + ldsw + _i * 8192), 16, 0, PG8_B_AUX); } while (0)
; #define PG8_LDA(dst, b, h) do { _Pragma("unroll") for (int m = 0; m < 4; ++m) _Pragma("unroll") for (int k = 0; k < 2; ++k) dst[m][k] = *(const PG8_LAS bf16x8*)(lds + PG8_SA(b, h) + aoff + m * 2048 + k * 1024); } while (0)
; #define PG8_LDB(dst, b, h) do { _Pragma("unroll") for (int n = 0; n < 2; ++n) _Pragma("unroll") for (int k = 0; k < 2; ++k) dst[n][k] = *(const PG8_LAS bf16x8*)(lds + PG8_SB(b, h) + boff + n * 2048 + k * 1024); } while (0)
; #define PG8_WAIT_V(n) asm volatile("s_waitcnt vmcnt(" #n ")" ::: "memory")
; template <class Epi, class Sched, bool ALIGN_EPI = false, bool SP2 = false>
; __device__ __forceinline__ void gemm_phase(PG8_LAS unsigned char* lds, const Gemm g, const Sched& S, const Epi& E, int wid) {
;     ...
;         for (int t = 0; t < nt; t += 2) {
;     ...
;             PG8_LDB(B0, 0, 0); PG8_LDB(B1, 0, 1); PG8_SCHED; PG8_LDA(At, 0, 0); PG8_STAGE(PG8_SA(1, 1), a1 + hstepA, voffA);
;             PG8_WAIT_V(8); PG8_WAIT_L(0); PG8_BAR; PG8_MMA(0, 0, At, B0); PG8_MMA(0, 1, At, B1); PG8_BAR; PG8_SCHED;
;             PG8_LDA(At, 0, 1); PG8_STAGE_NT(PG8_SB(0, 0), b2, voffB); PG8_STAGE_NT(PG8_SB(0, 1), b2 + hstepB, voffB); PG8_STAGE(PG8_SA(0, 0), a2, voffA);
;             PG8_WAIT_V(8); PG8_WAIT_L(0); PG8_BAR; PG8_MMA(1, 0, At, B0); PG8_MMA(1, 1, At, B1); PG8_BAR; PG8_SCHED;
;             PG8_LDB(B0, 1, 0); PG8_LDB(B1, 1, 1); PG8_SCHED; PG8_LDA(At, 1, 0); PG8_STAGE(PG8_SA(0, 1), a2 + hstepA, voffA);
;             PG8_WAIT_V(8); PG8_WAIT_L(0); PG8_BAR; PG8_MMA(0, 0, At, B0); PG8_MMA(0, 1, At, B1); PG8_BAR; PG8_SCHED;
;             PG8_LDA(At, 1, 1); PG8_STAGE_NT(PG8_SB(1, 0), b3, voffB); PG8_STAGE_NT(PG8_SB(1, 1), b3 + hstepB, voffB); PG8_STAGE(PG8_SA(1, 0), a3, voffA);
;             PG8_WAIT_V(8); PG8_WAIT_L(0); PG8_BAR; PG8_MMA(1, 0, At, B0); PG8_MMA(1, 1, At, B1); PG8_BAR; PG8_SCHED;
	s_add_i32 s46, s64, s9
	v_lshl_add_u64 v[200:201], v[200:201], 0, s[40:41]
	s_mov_b32 m0, s46
	ds_read_b128 v[160:163], v207 offset:49152
	ds_read_b128 v[164:167], v207 offset:50176
	ds_read_b128 v[184:187], v207 offset:51200
	ds_read_b128 v[188:191], v207 offset:52224
	ds_read_b128 v[192:195], v207 offset:53248
	ds_read_b128 v[196:199], v207 offset:54272
	ds_read_b128 v[210:213], v207 offset:55296
	ds_read_b128 v[214:217], v207 offset:56320
	global_load_lds_dwordx4 v[200:201], off
	s_add_i32 m0, s46, 0x2000
	s_add_u32 s46, s50, 0x2b4080
	v_lshl_add_u64 v[200:201], v[218:219], 0, s[40:41]
	s_addc_u32 s47, s51, 0
	s_add_i32 s50, s65, s9
	global_load_lds_dwordx4 v[200:201], off
	v_lshl_add_u64 v[200:201], s[46:47], 0, v[170:171]
	s_mov_b32 m0, s50
	s_nop 0
	global_load_lds_dwordx4 v[200:201], off
	v_lshl_add_u64 v[200:201], s[46:47], 0, v[174:175]
	s_add_i32 m0, s50, 0x2000
	s_nop 0
	global_load_lds_dwordx4 v[200:201], off
	v_lshl_add_u64 v[200:201], v[220:221], 0, s[40:41]
	s_mov_b32 m0, s25
	s_nop 0
	global_load_lds_dwordx4 v[200:201], off
	v_lshl_add_u64 v[200:201], v[222:223], 0, s[40:41]
	s_mov_b32 m0, s29
	s_nop 0
	global_load_lds_dwordx4 v[200:201], off
	s_nop 0
	s_waitcnt vmcnt(8)
	s_waitcnt lgkmcnt(0)
	s_barrier
	s_setprio 1
	v_mfma_f32_16x16x32_bf16 v[60:63], v[128:131], v[160:163], v[60:63]
	v_mfma_f32_16x16x32_bf16 v[56:59], v[136:139], v[160:163], v[56:59]
	v_mfma_f32_16x16x32_bf16 v[44:47], v[128:131], v[184:187], v[44:47]
	v_mfma_f32_16x16x32_bf16 v[40:43], v[136:139], v[184:187], v[40:43]
	v_mfma_f32_16x16x32_bf16 v[28:31], v[128:131], v[192:195], v[28:31]
	v_mfma_f32_16x16x32_bf16 v[24:27], v[136:139], v[192:195], v[24:27]
	v_mfma_f32_16x16x32_bf16 v[12:15], v[128:131], v[210:213], v[12:15]
	v_mfma_f32_16x16x32_bf16 v[8:11], v[136:139], v[210:213], v[8:11]
	v_mfma_f32_16x16x32_bf16 v[60:63], v[132:135], v[164:167], v[60:63]
	v_mfma_f32_16x16x32_bf16 v[56:59], v[140:143], v[164:167], v[56:59]
	v_mfma_f32_16x16x32_bf16 v[44:47], v[132:135], v[188:191], v[44:47]
	v_mfma_f32_16x16x32_bf16 v[40:43], v[140:143], v[188:191], v[40:43]
	v_mfma_f32_16x16x32_bf16 v[28:31], v[132:135], v[196:199], v[28:31]
	v_mfma_f32_16x16x32_bf16 v[24:27], v[140:143], v[196:199], v[24:27]
	v_mfma_f32_16x16x32_bf16 v[12:15], v[132:135], v[214:217], v[12:15]
	v_mfma_f32_16x16x32_bf16 v[8:11], v[140:143], v[214:217], v[8:11]
	s_setprio 0
	s_setprio 1
	v_mfma_f32_16x16x32_bf16 v[52:55], v[144:147], v[160:163], v[52:55]
	v_mfma_f32_16x16x32_bf16 v[48:51], v[152:155], v[160:163], v[48:51]
	v_mfma_f32_16x16x32_bf16 v[36:39], v[144:147], v[184:187], v[36:39]
	v_mfma_f32_16x16x32_bf16 v[32:35], v[152:155], v[184:187], v[32:35]
	v_mfma_f32_16x16x32_bf16 v[20:23], v[144:147], v[192:195], v[20:23]
	v_mfma_f32_16x16x32_bf16 v[16:19], v[152:155], v[192:195], v[16:19]
	v_mfma_f32_16x16x32_bf16 v[4:7], v[144:147], v[210:213], v[4:7]
	v_mfma_f32_16x16x32_bf16 v[0:3], v[152:155], v[210:213], v[0:3]
	v_mfma_f32_16x16x32_bf16 v[52:55], v[148:151], v[164:167], v[52:55]
	v_mfma_f32_16x16x32_bf16 v[48:51], v[156:159], v[164:167], v[48:51]
	v_mfma_f32_16x16x32_bf16 v[36:39], v[148:151], v[188:191], v[36:39]
	v_mfma_f32_16x16x32_bf16 v[32:35], v[156:159], v[188:191], v[32:35]
	v_mfma_f32_16x16x32_bf16 v[20:23], v[148:151], v[196:199], v[20:23]
	v_mfma_f32_16x16x32_bf16 v[16:19], v[156:159], v[196:199], v[16:19]
	v_mfma_f32_16x16x32_bf16 v[4:7], v[148:151], v[214:217], v[4:7]
	v_mfma_f32_16x16x32_bf16 v[0:3], v[156:159], v[214:217], v[0:3]
	s_setprio 0
	s_barrier
	s_add_i32 s63, s63, 2
	s_add_u32 s61, s61, 0x100
	s_addc_u32 s62, s62, 0
	s_cmpk_gt_u32 s63, 0xa9
	s_mov_b64 s[46:47], s[48:49]
	s_cbranch_scc0 .LBB0_1221
	s_and_b64 vcc, exec, s[42:43]
	s_cbranch_vccz .LBB0_1224
	s_barrier

; #define PG8_STAGE(bufoff, gbase, voff) do { _Pragma("unroll") for (int _i = 0; _i < 2; ++_i) \
;         __builtin_amdgcn_global_load_lds((const unsigned*)((const char*)(gbase) + (voff)[_i]), (PG8_LAS unsigned*)(lds + (bufoff) + ldsw + _i * 8192), 16, 0, 0); } while (0)
; #define PG8_STAGE_NT(bufoff, gbase, voff) do { _Pragma("unroll") for (int _i = 0; _i < 2; ++_i) \
;         __builtin_amdgcn_global_load_lds((const unsigned*)((const char*)(gbase) + (voff)[_i]), (PG8_LAS unsigned*)(lds + (bufoff) + ldsw + _i * 8192), 16, 0, PG8_B_AUX); } while (0)
; #define PG8_LDA(dst, b, h) do { _Pragma("unroll") for (int m = 0; m < 4; ++m) _Pragma("unroll") for (int k = 0; k < 2; ++k) dst[m][k] = *(const PG8_LAS bf16x8*)(lds + PG8_SA(b, h) + aoff + m * 2048 + k * 1024); } while (0)
; #define PG8_LDB(dst, b, h) do { _Pragma("unroll") for (int n = 0; n < 2; ++n) _Pragma("unroll") for (int k = 0; k < 2; ++k) dst[n][k] = *(const PG8_LAS bf16x8*)(lds + PG8_SB(b, h) + boff + n * 2048 + k * 1024); } while (0)
; #define PG8_MMA(ai, bj, At, Bt) do { __builtin_amdgcn_s_setprio(1); _Pragma("unroll") for (int m = 0; m < 4; ++m) _Pragma("unroll") for (int n = 0; n < 2; ++n) _Pragma("unroll") for (int k = 0; k < 2; ++k) \
;         acc[ai][bj][m][n] = __builtin_amdgcn_mfma_f32_16x16x32_bf16(Bt[n][k], At[m][k], acc[ai][bj][m][n], 0, 0, 0); __builtin_amdgcn_s_setprio(0); } while (0)
; #define PG8_WAIT_V(n) asm volatile("s_waitcnt vmcnt(" #n ")" ::: "memory")
; #define PG8_WAIT_L(n) asm volatile("s_waitcnt lgkmcnt(" #n ")" ::: "memory")
; #define PG8_BAR __builtin_amdgcn_s_barrier()
; #define PG8_SCHED __builtin_amdgcn_sched_barrier(0)
; template <class Epi, class Sched, bool ALIGN_EPI = false, bool SP2 = false>
; __device__ __forceinline__ void gemm_phase(PG8_LAS unsigned char* lds, const Gemm g, const Sched& S, const Epi& E, int wid) {
;     ...
;             PG8_LDB(B0, 0, 0); PG8_LDB(B1, 0, 1); PG8_SCHED; PG8_LDA(At, 0, 0); PG8_STAGE(PG8_SA(1, 1), a1 + hstepA, voffA);
;             PG8_WAIT_V(8); PG8_WAIT_L(0); PG8_BAR; PG8_MMA(0, 0, At, B0); PG8_MMA(0, 1, At, B1); PG8_BAR; PG8_SCHED;
;             PG8_LDA(At, 0, 1); PG8_STAGE_NT(PG8_SB(0, 0), b2, voffB); PG8_STAGE_NT(PG8_SB(0, 1), b2 + hstepB, voffB); PG8_STAGE(PG8_SA(0, 0), a2, voffA);
;             PG8_WAIT_V(8); PG8_WAIT_L(0); PG8_BAR; PG8_MMA(1, 0, At, B0); PG8_MMA(1, 1, At, B1); PG8_BAR; PG8_SCHED;
.LBB0_1249:
	ds_read_b128 v[146:149], v141
	ds_read_b128 v[150:153], v141 offset:1024
	ds_read_b128 v[154:157], v141 offset:2048
	ds_read_b128 v[158:161], v141 offset:3072
	ds_read_b128 v[162:165], v142
	ds_read_b128 v[166:169], v142 offset:1024
	ds_read_b128 v[170:173], v142 offset:2048
	ds_read_b128 v[174:177], v142 offset:3072
	s_add_u32 s46, s14, s50
	s_addc_u32 s47, s15, s51
	s_add_u32 s53, s14, s44
	s_addc_u32 s54, s15, s45
	s_cmpk_eq_i32 s52, 0xa8
	s_cselect_b32 s49, s3, s47
	s_cselect_b32 s48, s2, s46
	s_cselect_b32 s47, s11, s54
	s_cselect_b32 s46, s10, s53
	s_mov_b32 m0, s57
	v_lshl_add_u64 v[212:213], s[14:15], 0, v[136:137]
	ds_read_b128 v[178:181], v143
	ds_read_b128 v[182:185], v143 offset:1024
	ds_read_b128 v[186:189], v143 offset:2048
	ds_read_b128 v[190:193], v143 offset:3072
	ds_read_b128 v[194:197], v143 offset:4096
	ds_read_b128 v[198:201], v143 offset:5120
	ds_read_b128 v[202:205], v143 offset:6144
	ds_read_b128 v[208:211], v143 offset:7168
	global_load_lds_dwordx4 v[212:213], off
	v_lshl_add_u64 v[212:213], s[14:15], 0, v[138:139]
	s_mov_b32 m0, s58
	s_nop 0
	global_load_lds_dwordx4 v[212:213], off
	s_nop 0
	s_waitcnt vmcnt(8)
	s_waitcnt lgkmcnt(0)
	s_barrier
	s_setprio 1
	v_mfma_f32_16x16x32_bf16 v[124:127], v[146:149], v[178:181], v[124:127]
	v_mfma_f32_16x16x32_bf16 v[120:123], v[154:157], v[178:181], v[120:123]
	v_mfma_f32_16x16x32_bf16 v[108:111], v[146:149], v[186:189], v[108:111]
	v_mfma_f32_16x16x32_bf16 v[104:107], v[154:157], v[186:189], v[104:107]
	v_mfma_f32_16x16x32_bf16 v[92:95], v[146:149], v[194:197], v[92:95]
	v_mfma_f32_16x16x32_bf16 v[88:91], v[154:157], v[194:197], v[88:91]
	v_mfma_f32_16x16x32_bf16 v[76:79], v[146:149], v[202:205], v[76:79]
	v_mfma_f32_16x16x32_bf16 v[72:75], v[154:157], v[202:205], v[72:75]
	v_mfma_f32_16x16x32_bf16 v[124:127], v[150:153], v[182:185], v[124:127]
	v_mfma_f32_16x16x32_bf16 v[120:123], v[158:161], v[182:185], v[120:123]
	v_mfma_f32_16x16x32_bf16 v[108:111], v[150:153], v[190:193], v[108:111]
	v_mfma_f32_16x16x32_bf16 v[104:107], v[158:161], v[190:193], v[104:107]
	v_mfma_f32_16x16x32_bf16 v[92:95], v[150:153], v[198:201], v[92:95]
	v_mfma_f32_16x16x32_bf16 v[88:91], v[158:161], v[198:201], v[88:91]
	v_mfma_f32_16x16x32_bf16 v[76:79], v[150:153], v[208:211], v[76:79]
	v_mfma_f32_16x16x32_bf16 v[72:75], v[158:161], v[208:211], v[72:75]
	s_setprio 0
	s_setprio 1
	v_mfma_f32_16x16x32_bf16 v[116:119], v[162:165], v[178:181], v[116:119]
	v_mfma_f32_16x16x32_bf16 v[112:115], v[170:173], v[178:181], v[112:115]
	v_mfma_f32_16x16x32_bf16 v[100:103], v[162:165], v[186:189], v[100:103]
	v_mfma_f32_16x16x32_bf16 v[96:99], v[170:173], v[186:189], v[96:99]
	v_mfma_f32_16x16x32_bf16 v[84:87], v[162:165], v[194:197], v[84:87]
	v_mfma_f32_16x16x32_bf16 v[80:83], v[170:173], v[194:197], v[80:83]
	v_mfma_f32_16x16x32_bf16 v[68:71], v[162:165], v[202:205], v[68:71]
	v_mfma_f32_16x16x32_bf16 v[64:67], v[170:173], v[202:205], v[64:67]
	v_mfma_f32_16x16x32_bf16 v[116:119], v[166:169], v[182:185], v[116:119]
	v_mfma_f32_16x16x32_bf16 v[112:115], v[174:177], v[182:185], v[112:115]
	v_mfma_f32_16x16x32_bf16 v[100:103], v[166:169], v[190:193], v[100:103]
	v_mfma_f32_16x16x32_bf16 v[96:99], v[174:177], v[190:193], v[96:99]
	v_mfma_f32_16x16x32_bf16 v[84:87], v[166:169], v[198:201], v[84:87]
	v_mfma_f32_16x16x32_bf16 v[80:83], v[174:177], v[198:201], v[80:83]
	v_mfma_f32_16x16x32_bf16 v[68:71], v[166:169], v[208:211], v[68:71]
	v_mfma_f32_16x16x32_bf16 v[64:67], v[174:177], v[208:211], v[64:67]
	s_setprio 0
	s_barrier
	s_mov_b32 m0, s59
	v_lshl_add_u64 v[212:213], s[46:47], 0, v[130:131]
	s_add_u32 s54, s46, 0x2b4000
	ds_read_b128 v[178:181], v143 offset:16384
	ds_read_b128 v[182:185], v143 offset:17408
	ds_read_b128 v[186:189], v143 offset:18432
	ds_read_b128 v[190:193], v143 offset:19456
	ds_read_b128 v[194:197], v143 offset:20480
	ds_read_b128 v[198:201], v143 offset:21504
	ds_read_b128 v[202:205], v143 offset:22528
	ds_read_b128 v[208:211], v143 offset:23552
	global_load_lds_dwordx4 v[212:213], off
	v_lshl_add_u64 v[214:215], s[46:47], 0, v[134:135]
	s_mov_b32 m0, s60
	s_addc_u32 s55, s47, 0
	global_load_lds_dwordx4 v[214:215], off
	v_lshl_add_u64 v[216:217], s[54:55], 0, v[130:131]
	s_mov_b32 m0, s61
	v_lshl_add_u64 v[218:219], s[48:49], 0, v[132:133]
	global_load_lds_dwordx4 v[216:217], off
	v_lshl_add_u64 v[216:217], s[54:55], 0, v[134:135]
	s_mov_b32 m0, s62
	s_nop 0
	global_load_lds_dwordx4 v[216:217], off
	v_lshl_add_u64 v[216:217], s[48:49], 0, v[128:129]
	s_mov_b32 m0, s17
	s_nop 0
	global_load_lds_dwordx4 v[216:217], off
	s_mov_b32 m0, s19
	s_nop 0
	global_load_lds_dwordx4 v[218:219], off
	s_waitcnt vmcnt(8)
	s_waitcnt lgkmcnt(0)
	s_barrier
; #define PG8_STAGE(bufoff, gbase, voff) do { _Pragma("unroll") for (int _i = 0; _i < 2; ++_i) \
;         __builtin_amdgcn_global_load_lds((const unsigned*)((const char*)(gbase) + (voff)[_i]), (PG8_LAS unsigned*)(lds + (bufoff) + ldsw + _i * 8192), 16, 0, 0); } while (0)
; #define PG8_LDA(dst, b, h) do { _Pragma("unroll") for (int m = 0; m < 4; ++m) _Pragma("unroll") for (int k = 0; k < 2; ++k) dst[m][k] = *(const PG8_LAS bf16x8*)(lds + PG8_SA(b, h) + aoff + m * 2048 + k * 1024); } while (0)
; #define PG8_LDB(dst, b, h) do { _Pragma("unroll") for (int n = 0; n < 2; ++n) _Pragma("unroll") for (int k = 0; k < 2; ++k) dst[n][k] = *(const PG8_LAS bf16x8*)(lds + PG8_SB(b, h) + boff + n * 2048 + k * 1024); } while (0)
; #define PG8_MMA(ai, bj, At, Bt) do { __builtin_amdgcn_s_setprio(1); _Pragma("unroll") for (int m = 0; m < 4; ++m) _Pragma("unroll") for (int n = 0; n < 2; ++n) _Pragma("unroll") for (int k = 0; k < 2; ++k) \
;         acc[ai][bj][m][n] = __builtin_amdgcn_mfma_f32_16x16x32_bf16(Bt[n][k], At[m][k], acc[ai][bj][m][n], 0, 0, 0); __builtin_amdgcn_s_setprio(0); } while (0)
; #define PG8_WAIT_V(n) asm volatile("s_waitcnt vmcnt(" #n ")" ::: "memory")
; #define PG8_WAIT_L(n) asm volatile("s_waitcnt lgkmcnt(" #n ")" ::: "memory")
; #define PG8_BAR __builtin_amdgcn_s_barrier()
; #define PG8_SCHED __builtin_amdgcn_sched_barrier(0)
; template <class Epi, class Sched, bool ALIGN_EPI = false, bool SP2 = false>
; __device__ __forceinline__ void gemm_phase(PG8_LAS unsigned char* lds, const Gemm g, const Sched& S, const Epi& E, int wid) {
;     ...
;             PG8_WAIT_V(8); PG8_WAIT_L(0); PG8_BAR; PG8_MMA(1, 0, At, B0); PG8_MMA(1, 1, At, B1); PG8_BAR; PG8_SCHED;
;             PG8_LDB(B0, 1, 0); PG8_LDB(B1, 1, 1); PG8_SCHED; PG8_LDA(At, 1, 0); PG8_STAGE(PG8_SA(0, 1), a2 + hstepA, voffA);
;             PG8_WAIT_V(8); PG8_WAIT_L(0); PG8_BAR; PG8_MMA(0, 0, At, B0); PG8_MMA(0, 1, At, B1); PG8_BAR; PG8_SCHED;
	s_setprio 1
	v_mfma_f32_16x16x32_bf16 v[60:63], v[146:149], v[178:181], v[60:63]
	v_mfma_f32_16x16x32_bf16 v[56:59], v[154:157], v[178:181], v[56:59]
	v_mfma_f32_16x16x32_bf16 v[44:47], v[146:149], v[186:189], v[44:47]
	v_mfma_f32_16x16x32_bf16 v[40:43], v[154:157], v[186:189], v[40:43]
	v_mfma_f32_16x16x32_bf16 v[28:31], v[146:149], v[194:197], v[28:31]
	v_mfma_f32_16x16x32_bf16 v[24:27], v[154:157], v[194:197], v[24:27]
	v_mfma_f32_16x16x32_bf16 v[12:15], v[146:149], v[202:205], v[12:15]
	v_mfma_f32_16x16x32_bf16 v[8:11], v[154:157], v[202:205], v[8:11]
	v_mfma_f32_16x16x32_bf16 v[60:63], v[150:153], v[182:185], v[60:63]
	v_mfma_f32_16x16x32_bf16 v[56:59], v[158:161], v[182:185], v[56:59]
	v_mfma_f32_16x16x32_bf16 v[44:47], v[150:153], v[190:193], v[44:47]
	v_mfma_f32_16x16x32_bf16 v[40:43], v[158:161], v[190:193], v[40:43]
	v_mfma_f32_16x16x32_bf16 v[28:31], v[150:153], v[198:201], v[28:31]
	v_mfma_f32_16x16x32_bf16 v[24:27], v[158:161], v[198:201], v[24:27]
	v_mfma_f32_16x16x32_bf16 v[12:15], v[150:153], v[208:211], v[12:15]
	v_mfma_f32_16x16x32_bf16 v[8:11], v[158:161], v[208:211], v[8:11]
	s_setprio 0
	s_setprio 1
	v_mfma_f32_16x16x32_bf16 v[52:55], v[162:165], v[178:181], v[52:55]
	v_mfma_f32_16x16x32_bf16 v[48:51], v[170:173], v[178:181], v[48:51]
	v_mfma_f32_16x16x32_bf16 v[36:39], v[162:165], v[186:189], v[36:39]
	v_mfma_f32_16x16x32_bf16 v[32:35], v[170:173], v[186:189], v[32:35]
	v_mfma_f32_16x16x32_bf16 v[20:23], v[162:165], v[194:197], v[20:23]
	v_mfma_f32_16x16x32_bf16 v[16:19], v[170:173], v[194:197], v[16:19]
	v_mfma_f32_16x16x32_bf16 v[4:7], v[162:165], v[202:205], v[4:7]
	v_mfma_f32_16x16x32_bf16 v[0:3], v[170:173], v[202:205], v[0:3]
	v_mfma_f32_16x16x32_bf16 v[52:55], v[166:169], v[182:185], v[52:55]
	v_mfma_f32_16x16x32_bf16 v[48:51], v[174:177], v[182:185], v[48:51]
	v_mfma_f32_16x16x32_bf16 v[36:39], v[166:169], v[190:193], v[36:39]
	v_mfma_f32_16x16x32_bf16 v[32:35], v[174:177], v[190:193], v[32:35]
	v_mfma_f32_16x16x32_bf16 v[20:23], v[166:169], v[198:201], v[20:23]
	v_mfma_f32_16x16x32_bf16 v[16:19], v[174:177], v[198:201], v[16:19]
	v_mfma_f32_16x16x32_bf16 v[4:7], v[166:169], v[208:211], v[4:7]
	v_mfma_f32_16x16x32_bf16 v[0:3], v[174:177], v[208:211], v[0:3]
	s_setprio 0
	s_barrier
	ds_read_b128 v[146:149], v144
	ds_read_b128 v[150:153], v144 offset:1024
	ds_read_b128 v[154:157], v144 offset:2048
	ds_read_b128 v[158:161], v144 offset:3072
	ds_read_b128 v[162:165], v145
	ds_read_b128 v[166:169], v145 offset:1024
	ds_read_b128 v[170:173], v145 offset:2048
	ds_read_b128 v[174:177], v145 offset:3072
	s_add_u32 s48, s48, 0x2b4000
	s_addc_u32 s49, s49, 0
	s_mov_b32 m0, s22
	v_lshl_add_u64 v[220:221], s[48:49], 0, v[128:129]
	ds_read_b128 v[178:181], v143 offset:32768
	ds_read_b128 v[182:185], v143 offset:33792
	ds_read_b128 v[186:189], v143 offset:34816
	ds_read_b128 v[190:193], v143 offset:35840
	ds_read_b128 v[194:197], v143 offset:36864
	ds_read_b128 v[198:201], v143 offset:37888
	ds_read_b128 v[202:205], v143 offset:38912
	ds_read_b128 v[208:211], v143 offset:39936
	global_load_lds_dwordx4 v[220:221], off
	v_lshl_add_u64 v[220:221], s[48:49], 0, v[132:133]
	s_mov_b32 m0, s23
	s_nop 0
	global_load_lds_dwordx4 v[220:221], off
	s_waitcnt vmcnt(8)
	s_waitcnt lgkmcnt(0)
	s_barrier
	s_setprio 1
	v_mfma_f32_16x16x32_bf16 v[124:127], v[146:149], v[178:181], v[124:127]
	v_mfma_f32_16x16x32_bf16 v[120:123], v[154:157], v[178:181], v[120:123]
	v_mfma_f32_16x16x32_bf16 v[108:111], v[146:149], v[186:189], v[108:111]
	v_mfma_f32_16x16x32_bf16 v[104:107], v[154:157], v[186:189], v[104:107]
	v_mfma_f32_16x16x32_bf16 v[92:95], v[146:149], v[194:197], v[92:95]
	v_mfma_f32_16x16x32_bf16 v[88:91], v[154:157], v[194:197], v[88:91]
	v_mfma_f32_16x16x32_bf16 v[76:79], v[146:149], v[202:205], v[76:79]
	v_mfma_f32_16x16x32_bf16 v[72:75], v[154:157], v[202:205], v[72:75]
	v_mfma_f32_16x16x32_bf16 v[124:127], v[150:153], v[182:185], v[124:127]
	v_mfma_f32_16x16x32_bf16 v[120:123], v[158:161], v[182:185], v[120:123]
	v_mfma_f32_16x16x32_bf16 v[108:111], v[150:153], v[190:193], v[108:111]
	v_mfma_f32_16x16x32_bf16 v[104:107], v[158:161], v[190:193], v[104:107]
	v_mfma_f32_16x16x32_bf16 v[92:95], v[150:153], v[198:201], v[92:95]
	v_mfma_f32_16x16x32_bf16 v[88:91], v[158:161], v[198:201], v[88:91]
	v_mfma_f32_16x16x32_bf16 v[76:79], v[150:153], v[208:211], v[76:79]
	v_mfma_f32_16x16x32_bf16 v[72:75], v[158:161], v[208:211], v[72:75]
	s_setprio 0
	s_setprio 1
	v_mfma_f32_16x16x32_bf16 v[116:119], v[162:165], v[178:181], v[116:119]
	v_mfma_f32_16x16x32_bf16 v[112:115], v[170:173], v[178:181], v[112:115]
	v_mfma_f32_16x16x32_bf16 v[100:103], v[162:165], v[186:189], v[100:103]
	v_mfma_f32_16x16x32_bf16 v[96:99], v[170:173], v[186:189], v[96:99]
	v_mfma_f32_16x16x32_bf16 v[84:87], v[162:165], v[194:197], v[84:87]
	v_mfma_f32_16x16x32_bf16 v[80:83], v[170:173], v[194:197], v[80:83]
	v_mfma_f32_16x16x32_bf16 v[68:71], v[162:165], v[202:205], v[68:71]
	v_mfma_f32_16x16x32_bf16 v[64:67], v[170:173], v[202:205], v[64:67]
	v_mfma_f32_16x16x32_bf16 v[116:119], v[166:169], v[182:185], v[116:119]
	v_mfma_f32_16x16x32_bf16 v[112:115], v[174:177], v[182:185], v[112:115]
	v_mfma_f32_16x16x32_bf16 v[100:103], v[166:169], v[190:193], v[100:103]
	v_mfma_f32_16x16x32_bf16 v[96:99], v[174:177], v[190:193], v[96:99]
	v_mfma_f32_16x16x32_bf16 v[84:87], v[166:169], v[198:201], v[84:87]
	v_mfma_f32_16x16x32_bf16 v[80:83], v[174:177], v[198:201], v[80:83]
	v_mfma_f32_16x16x32_bf16 v[68:71], v[166:169], v[208:211], v[68:71]
	v_mfma_f32_16x16x32_bf16 v[64:67], v[174:177], v[208:211], v[64:67]
	s_setprio 0
	s_barrier
; #define PG8_STAGE(bufoff, gbase, voff) do { _Pragma("unroll") for (int _i = 0; _i < 2; ++_i) \
;         __builtin_amdgcn_global_load_lds((const unsigned*)((const char*)(gbase) + (voff)[_i]), (PG8_LAS unsigned*)(lds + (bufoff) + ldsw + _i * 8192), 16, 0, 0); } while (0)
; #define PG8_STAGE_NT(bufoff, gbase, voff) do { _Pragma("unroll") for (int _i = 0; _i < 2; ++_i) \
;         __builtin_amdgcn_global_load_lds((const unsigned*)((const char*)(gbase) + (voff)[_i]), (PG8_LAS unsigned*)(lds + (bufoff) + ldsw + _i * 8192), 16, 0, PG8_B_AUX); } while (0)
; #define PG8_LDA(dst, b, h) do { _Pragma("unroll") for (int m = 0; m < 4; ++m) _Pragma("unroll") for (int k = 0; k < 2; ++k) dst[m][k] = *(const PG8_LAS bf16x8*)(lds + PG8_SA(b, h) + aoff + m * 2048 + k * 1024); } while (0)
; #define PG8_MMA(ai, bj, At, Bt) do { __builtin_amdgcn_s_setprio(1); _Pragma("unroll") for (int m = 0; m < 4; ++m) _Pragma("unroll") for (int n = 0; n < 2; ++n) _Pragma("unroll") for (int k = 0; k < 2; ++k) \
;         acc[ai][bj][m][n] = __builtin_amdgcn_mfma_f32_16x16x32_bf16(Bt[n][k], At[m][k], acc[ai][bj][m][n], 0, 0, 0); __builtin_amdgcn_s_setprio(0); } while (0)
; #define PG8_WAIT_V(n) asm volatile("s_waitcnt vmcnt(" #n ")" ::: "memory")
; #define PG8_WAIT_L(n) asm volatile("s_waitcnt lgkmcnt(" #n ")" ::: "memory")
; #define PG8_BAR __builtin_amdgcn_s_barrier()
; #define PG8_SCHED __builtin_amdgcn_sched_barrier(0)
; template <class Epi, class Sched, bool ALIGN_EPI = false, bool SP2 = false>
; __device__ __forceinline__ void gemm_phase(PG8_LAS unsigned char* lds, const Gemm g, const Sched& S, const Epi& E, int wid) {
;     ...
;             PG8_LDA(At, 1, 1); PG8_STAGE_NT(PG8_SB(1, 0), b3, voffB); PG8_STAGE_NT(PG8_SB(1, 1), b3 + hstepB, voffB); PG8_STAGE(PG8_SA(1, 0), a3, voffA);
;             PG8_WAIT_V(8); PG8_WAIT_L(0); PG8_BAR; PG8_MMA(1, 0, At, B0); PG8_MMA(1, 1, At, B1); PG8_BAR; PG8_SCHED;
;     ...
;     PG8_WAIT_V(0);
;     if constexpr (!ALIGN_EPI) { if (wr == 0) PG8_BAR; }
	s_mov_b32 m0, s63
	v_lshl_add_u64 v[212:213], v[212:213], 0, s[4:5]
	s_add_u32 s46, s46, 0x2b4080
	ds_read_b128 v[178:181], v143 offset:49152
	ds_read_b128 v[182:185], v143 offset:50176
	ds_read_b128 v[186:189], v143 offset:51200
	ds_read_b128 v[190:193], v143 offset:52224
	ds_read_b128 v[194:197], v143 offset:53248
	ds_read_b128 v[198:201], v143 offset:54272
	ds_read_b128 v[202:205], v143 offset:55296
	ds_read_b128 v[208:211], v143 offset:56320
	global_load_lds_dwordx4 v[212:213], off
	v_lshl_add_u64 v[212:213], v[214:215], 0, s[4:5]
	s_mov_b32 m0, s64
	s_addc_u32 s47, s47, 0
	global_load_lds_dwordx4 v[212:213], off
	v_lshl_add_u64 v[212:213], s[46:47], 0, v[130:131]
	s_mov_b32 m0, s65
	s_nop 0
	global_load_lds_dwordx4 v[212:213], off
	v_lshl_add_u64 v[212:213], s[46:47], 0, v[134:135]
	s_mov_b32 m0, s66
	s_nop 0
	global_load_lds_dwordx4 v[212:213], off
	v_lshl_add_u64 v[212:213], v[216:217], 0, s[4:5]
	s_mov_b32 m0, s25
	s_nop 0
	global_load_lds_dwordx4 v[212:213], off
	v_lshl_add_u64 v[212:213], v[218:219], 0, s[4:5]
	s_mov_b32 m0, s56
	s_nop 0
	global_load_lds_dwordx4 v[212:213], off
	s_nop 0
	s_waitcnt vmcnt(8)
	s_waitcnt lgkmcnt(0)
	s_barrier
	s_setprio 1
	v_mfma_f32_16x16x32_bf16 v[60:63], v[146:149], v[178:181], v[60:63]
	v_mfma_f32_16x16x32_bf16 v[56:59], v[154:157], v[178:181], v[56:59]
	v_mfma_f32_16x16x32_bf16 v[44:47], v[146:149], v[186:189], v[44:47]
	v_mfma_f32_16x16x32_bf16 v[40:43], v[154:157], v[186:189], v[40:43]
	v_mfma_f32_16x16x32_bf16 v[28:31], v[146:149], v[194:197], v[28:31]
	v_mfma_f32_16x16x32_bf16 v[24:27], v[154:157], v[194:197], v[24:27]
	v_mfma_f32_16x16x32_bf16 v[12:15], v[146:149], v[202:205], v[12:15]
	v_mfma_f32_16x16x32_bf16 v[8:11], v[154:157], v[202:205], v[8:11]
	v_mfma_f32_16x16x32_bf16 v[60:63], v[150:153], v[182:185], v[60:63]
	v_mfma_f32_16x16x32_bf16 v[56:59], v[158:161], v[182:185], v[56:59]
	v_mfma_f32_16x16x32_bf16 v[44:47], v[150:153], v[190:193], v[44:47]
	v_mfma_f32_16x16x32_bf16 v[40:43], v[158:161], v[190:193], v[40:43]
	v_mfma_f32_16x16x32_bf16 v[28:31], v[150:153], v[198:201], v[28:31]
	v_mfma_f32_16x16x32_bf16 v[24:27], v[158:161], v[198:201], v[24:27]
	v_mfma_f32_16x16x32_bf16 v[12:15], v[150:153], v[208:211], v[12:15]
	v_mfma_f32_16x16x32_bf16 v[8:11], v[158:161], v[208:211], v[8:11]
	s_setprio 0
	s_setprio 1
	v_mfma_f32_16x16x32_bf16 v[52:55], v[162:165], v[178:181], v[52:55]
	v_mfma_f32_16x16x32_bf16 v[48:51], v[170:173], v[178:181], v[48:51]
	v_mfma_f32_16x16x32_bf16 v[36:39], v[162:165], v[186:189], v[36:39]
	v_mfma_f32_16x16x32_bf16 v[32:35], v[170:173], v[186:189], v[32:35]
	v_mfma_f32_16x16x32_bf16 v[20:23], v[162:165], v[194:197], v[20:23]
	v_mfma_f32_16x16x32_bf16 v[16:19], v[170:173], v[194:197], v[16:19]
	v_mfma_f32_16x16x32_bf16 v[4:7], v[162:165], v[202:205], v[4:7]
	v_mfma_f32_16x16x32_bf16 v[0:3], v[170:173], v[202:205], v[0:3]
	v_mfma_f32_16x16x32_bf16 v[52:55], v[166:169], v[182:185], v[52:55]
	v_mfma_f32_16x16x32_bf16 v[48:51], v[174:177], v[182:185], v[48:51]
	v_mfma_f32_16x16x32_bf16 v[36:39], v[166:169], v[190:193], v[36:39]
	v_mfma_f32_16x16x32_bf16 v[32:35], v[174:177], v[190:193], v[32:35]
	v_mfma_f32_16x16x32_bf16 v[20:23], v[166:169], v[198:201], v[20:23]
	v_mfma_f32_16x16x32_bf16 v[16:19], v[174:177], v[198:201], v[16:19]
	v_mfma_f32_16x16x32_bf16 v[4:7], v[166:169], v[208:211], v[4:7]
	v_mfma_f32_16x16x32_bf16 v[0:3], v[174:177], v[208:211], v[0:3]
	s_setprio 0
	s_barrier
	s_add_i32 s52, s52, 2
	s_add_u32 s50, s50, 0x100
	s_addc_u32 s51, s51, 0
	s_add_u32 s44, s44, 0x100
	s_addc_u32 s45, s45, 0
	v_lshl_add_u64 v[136:137], v[136:137], 0, s[42:43]
	s_cmpk_lt_u32 s52, 0xaa
	v_lshl_add_u64 v[138:139], v[138:139], 0, s[42:43]
	s_cbranch_scc1 .LBB0_1249
	s_waitcnt vmcnt(0)
	s_cmpk_lt_u32 s95, 0x100
	s_cselect_b64 s[44:45], -1, 0
	s_cmpk_gt_u32 s95, 0xff
	s_cbranch_scc1 .LBB0_1252
	s_barrier

; #define PG8_STAGE(bufoff, gbase, voff) do { _Pragma("unroll") for (int _i = 0; _i < 2; ++_i) \
;         __builtin_amdgcn_global_load_lds((const unsigned*)((const char*)(gbase) + (voff)[_i]), (PG8_LAS unsigned*)(lds + (bufoff) + ldsw + _i * 8192), 16, 0, 0); } while (0)
; #define PG8_STAGE_NT(bufoff, gbase, voff) do { _Pragma("unroll") for (int _i = 0; _i < 2; ++_i) \
;         __builtin_amdgcn_global_load_lds((const unsigned*)((const char*)(gbase) + (voff)[_i]), (PG8_LAS unsigned*)(lds + (bufoff) + ldsw + _i * 8192), 16, 0, PG8_B_AUX); } while (0)
; #define PG8_LDA(dst, b, h) do { _Pragma("unroll") for (int m = 0; m < 4; ++m) _Pragma("unroll") for (int k = 0; k < 2; ++k) dst[m][k] = *(const PG8_LAS bf16x8*)(lds + PG8_SA(b, h) + aoff + m * 2048 + k * 1024); } while (0)
; #define PG8_LDB(dst, b, h) do { _Pragma("unroll") for (int n = 0; n < 2; ++n) _Pragma("unroll") for (int k = 0; k < 2; ++k) dst[n][k] = *(const PG8_LAS bf16x8*)(lds + PG8_SB(b, h) + boff + n * 2048 + k * 1024); } while (0)
; #define PG8_MMA(ai, bj, At, Bt) do { __builtin_amdgcn_s_setprio(1); _Pragma("unroll") for (int m = 0; m < 4; ++m) _Pragma("unroll") for (int n = 0; n < 2; ++n) _Pragma("unroll") for (int k = 0; k < 2; ++k) \
;         acc[ai][bj][m][n] = __builtin_amdgcn_mfma_f32_16x16x32_bf16(Bt[n][k], At[m][k], acc[ai][bj][m][n], 0, 0, 0); __builtin_amdgcn_s_setprio(0); } while (0)
; #define PG8_WAIT_V(n) asm volatile("s_waitcnt vmcnt(" #n ")" ::: "memory")
; #define PG8_WAIT_L(n) asm volatile("s_waitcnt lgkmcnt(" #n ")" ::: "memory")
; #define PG8_BAR __builtin_amdgcn_s_barrier()
; #define PG8_SCHED __builtin_amdgcn_sched_barrier(0)
; template <class Epi, class Sched, bool ALIGN_EPI = false, bool SP2 = false>
; __device__ __forceinline__ void gemm_phase(PG8_LAS unsigned char* lds, const Gemm g, const Sched& S, const Epi& E, int wid) {
;     ...
;             PG8_LDB(B0, 0, 0); PG8_LDB(B1, 0, 1); PG8_SCHED; PG8_LDA(At, 0, 0); PG8_STAGE(PG8_SA(1, 1), a1 + hstepA, voffA);
;             PG8_WAIT_V(8); PG8_WAIT_L(0); PG8_BAR; PG8_MMA(0, 0, At, B0); PG8_MMA(0, 1, At, B1); PG8_BAR; PG8_SCHED;
;             PG8_LDA(At, 0, 1); PG8_STAGE_NT(PG8_SB(0, 0), b2, voffB); PG8_STAGE_NT(PG8_SB(0, 1), b2 + hstepB, voffB); PG8_STAGE(PG8_SA(0, 0), a2, voffA);
;             PG8_WAIT_V(8); PG8_WAIT_L(0); PG8_BAR; PG8_MMA(1, 0, At, B0); PG8_MMA(1, 1, At, B1); PG8_BAR; PG8_SCHED;
.LBB0_1307:
	ds_read_b128 v[146:149], v141
	ds_read_b128 v[150:153], v141 offset:1024
	ds_read_b128 v[154:157], v141 offset:2048
	ds_read_b128 v[158:161], v141 offset:3072
	ds_read_b128 v[162:165], v142
	ds_read_b128 v[166:169], v142 offset:1024
	ds_read_b128 v[170:173], v142 offset:2048
	ds_read_b128 v[174:177], v142 offset:3072
	s_add_u32 s30, s14, s21
	s_addc_u32 s31, s15, s40
	s_add_u32 s48, s14, s8
	s_addc_u32 s49, s15, s9
	s_cmpk_eq_i32 s41, 0xa8
	s_cselect_b32 s39, s3, s31
	s_cselect_b32 s38, s2, s30
	s_cselect_b32 s31, s11, s49
	s_cselect_b32 s30, s10, s48
	s_mov_b32 m0, s57
	v_lshl_add_u64 v[202:203], s[14:15], 0, v[136:137]
	ds_read_b128 v[178:181], v143
	ds_read_b128 v[182:185], v143 offset:1024
	ds_read_b128 v[186:189], v143 offset:2048
	ds_read_b128 v[190:193], v143 offset:3072
	ds_read_b128 v[194:197], v143 offset:4096
	ds_read_b128 v[198:201], v143 offset:5120
	ds_read_b128 v[208:211], v143 offset:6144
	ds_read_b128 v[212:215], v143 offset:7168
	global_load_lds_dwordx4 v[202:203], off
	v_lshl_add_u64 v[202:203], s[14:15], 0, v[138:139]
	s_mov_b32 m0, s58
	s_nop 0
	global_load_lds_dwordx4 v[202:203], off
	s_nop 0
	s_waitcnt vmcnt(8)
	s_waitcnt lgkmcnt(0)
	s_barrier
	s_setprio 1
	v_mfma_f32_16x16x32_bf16 v[124:127], v[146:149], v[178:181], v[124:127]
	v_mfma_f32_16x16x32_bf16 v[120:123], v[154:157], v[178:181], v[120:123]
	v_mfma_f32_16x16x32_bf16 v[108:111], v[146:149], v[186:189], v[108:111]
	v_mfma_f32_16x16x32_bf16 v[104:107], v[154:157], v[186:189], v[104:107]
	v_mfma_f32_16x16x32_bf16 v[92:95], v[146:149], v[194:197], v[92:95]
	v_mfma_f32_16x16x32_bf16 v[88:91], v[154:157], v[194:197], v[88:91]
	v_mfma_f32_16x16x32_bf16 v[76:79], v[146:149], v[208:211], v[76:79]
	v_mfma_f32_16x16x32_bf16 v[72:75], v[154:157], v[208:211], v[72:75]
	v_mfma_f32_16x16x32_bf16 v[124:127], v[150:153], v[182:185], v[124:127]
	v_mfma_f32_16x16x32_bf16 v[120:123], v[158:161], v[182:185], v[120:123]
	v_mfma_f32_16x16x32_bf16 v[108:111], v[150:153], v[190:193], v[108:111]
	v_mfma_f32_16x16x32_bf16 v[104:107], v[158:161], v[190:193], v[104:107]
	v_mfma_f32_16x16x32_bf16 v[92:95], v[150:153], v[198:201], v[92:95]
	v_mfma_f32_16x16x32_bf16 v[88:91], v[158:161], v[198:201], v[88:91]
	v_mfma_f32_16x16x32_bf16 v[76:79], v[150:153], v[212:215], v[76:79]
	v_mfma_f32_16x16x32_bf16 v[72:75], v[158:161], v[212:215], v[72:75]
	s_setprio 0
	s_setprio 1
	v_mfma_f32_16x16x32_bf16 v[116:119], v[162:165], v[178:181], v[116:119]
	v_mfma_f32_16x16x32_bf16 v[112:115], v[170:173], v[178:181], v[112:115]
	v_mfma_f32_16x16x32_bf16 v[100:103], v[162:165], v[186:189], v[100:103]
	v_mfma_f32_16x16x32_bf16 v[96:99], v[170:173], v[186:189], v[96:99]
	v_mfma_f32_16x16x32_bf16 v[84:87], v[162:165], v[194:197], v[84:87]
	v_mfma_f32_16x16x32_bf16 v[80:83], v[170:173], v[194:197], v[80:83]
	v_mfma_f32_16x16x32_bf16 v[68:71], v[162:165], v[208:211], v[68:71]
	v_mfma_f32_16x16x32_bf16 v[64:67], v[170:173], v[208:211], v[64:67]
	v_mfma_f32_16x16x32_bf16 v[116:119], v[166:169], v[182:185], v[116:119]
	v_mfma_f32_16x16x32_bf16 v[112:115], v[174:177], v[182:185], v[112:115]
	v_mfma_f32_16x16x32_bf16 v[100:103], v[166:169], v[190:193], v[100:103]
	v_mfma_f32_16x16x32_bf16 v[96:99], v[174:177], v[190:193], v[96:99]
	v_mfma_f32_16x16x32_bf16 v[84:87], v[166:169], v[198:201], v[84:87]
	v_mfma_f32_16x16x32_bf16 v[80:83], v[174:177], v[198:201], v[80:83]
	v_mfma_f32_16x16x32_bf16 v[68:71], v[166:169], v[212:215], v[68:71]
	v_mfma_f32_16x16x32_bf16 v[64:67], v[174:177], v[212:215], v[64:67]
	s_setprio 0
	s_barrier
	s_mov_b32 m0, s59
	v_lshl_add_u64 v[202:203], s[30:31], 0, v[130:131]
	s_add_u32 s48, s30, 0x2b4000
	ds_read_b128 v[178:181], v143 offset:16384
	ds_read_b128 v[182:185], v143 offset:17408
	ds_read_b128 v[186:189], v143 offset:18432
	ds_read_b128 v[190:193], v143 offset:19456
	ds_read_b128 v[194:197], v143 offset:20480
	ds_read_b128 v[198:201], v143 offset:21504
	ds_read_b128 v[208:211], v143 offset:22528
	ds_read_b128 v[212:215], v143 offset:23552
	global_load_lds_dwordx4 v[202:203], off
	v_lshl_add_u64 v[216:217], s[30:31], 0, v[134:135]
	s_mov_b32 m0, s60
	s_addc_u32 s49, s31, 0
	global_load_lds_dwordx4 v[216:217], off
	v_lshl_add_u64 v[218:219], s[48:49], 0, v[130:131]
	s_mov_b32 m0, s61
	v_lshl_add_u64 v[220:221], s[38:39], 0, v[132:133]
	global_load_lds_dwordx4 v[218:219], off
	v_lshl_add_u64 v[218:219], s[48:49], 0, v[134:135]
	s_mov_b32 m0, s62
	s_nop 0
	global_load_lds_dwordx4 v[218:219], off
	v_lshl_add_u64 v[218:219], s[38:39], 0, v[128:129]
	s_mov_b32 m0, s17
	s_nop 0
	global_load_lds_dwordx4 v[218:219], off
	s_mov_b32 m0, s19
	s_nop 0
	global_load_lds_dwordx4 v[220:221], off
	s_waitcnt vmcnt(8)
	s_waitcnt lgkmcnt(0)
	s_barrier
; #define PG8_STAGE(bufoff, gbase, voff) do { _Pragma("unroll") for (int _i = 0; _i < 2; ++_i) \
;         __builtin_amdgcn_global_load_lds((const unsigned*)((const char*)(gbase) + (voff)[_i]), (PG8_LAS unsigned*)(lds + (bufoff) + ldsw + _i * 8192), 16, 0, 0); } while (0)
; #define PG8_LDA(dst, b, h) do { _Pragma("unroll") for (int m = 0; m < 4; ++m) _Pragma("unroll") for (int k = 0; k < 2; ++k) dst[m][k] = *(const PG8_LAS bf16x8*)(lds + PG8_SA(b, h) + aoff + m * 2048 + k * 1024); } while (0)
; #define PG8_LDB(dst, b, h) do { _Pragma("unroll") for (int n = 0; n < 2; ++n) _Pragma("unroll") for (int k = 0; k < 2; ++k) dst[n][k] = *(const PG8_LAS bf16x8*)(lds + PG8_SB(b, h) + boff + n * 2048 + k * 1024); } while (0)
; #define PG8_MMA(ai, bj, At, Bt) do { __builtin_amdgcn_s_setprio(1); _Pragma("unroll") for (int m = 0; m < 4; ++m) _Pragma("unroll") for (int n = 0; n < 2; ++n) _Pragma("unroll") for (int k = 0; k < 2; ++k) \
;         acc[ai][bj][m][n] = __builtin_amdgcn_mfma_f32_16x16x32_bf16(Bt[n][k], At[m][k], acc[ai][bj][m][n], 0, 0, 0); __builtin_amdgcn_s_setprio(0); } while (0)
; #define PG8_WAIT_V(n) asm volatile("s_waitcnt vmcnt(" #n ")" ::: "memory")
; #define PG8_WAIT_L(n) asm volatile("s_waitcnt lgkmcnt(" #n ")" ::: "memory")
; #define PG8_BAR __builtin_amdgcn_s_barrier()
; #define PG8_SCHED __builtin_amdgcn_sched_barrier(0)
; template <class Epi, class Sched, bool ALIGN_EPI = false, bool SP2 = false>
; __device__ __forceinline__ void gemm_phase(PG8_LAS unsigned char* lds, const Gemm g, const Sched& S, const Epi& E, int wid) {
;     ...
;             PG8_WAIT_V(8); PG8_WAIT_L(0); PG8_BAR; PG8_MMA(1, 0, At, B0); PG8_MMA(1, 1, At, B1); PG8_BAR; PG8_SCHED;
;             PG8_LDB(B0, 1, 0); PG8_LDB(B1, 1, 1); PG8_SCHED; PG8_LDA(At, 1, 0); PG8_STAGE(PG8_SA(0, 1), a2 + hstepA, voffA);
;             PG8_WAIT_V(8); PG8_WAIT_L(0); PG8_BAR; PG8_MMA(0, 0, At, B0); PG8_MMA(0, 1, At, B1); PG8_BAR; PG8_SCHED;
	s_setprio 1
	v_mfma_f32_16x16x32_bf16 v[60:63], v[146:149], v[178:181], v[60:63]
	v_mfma_f32_16x16x32_bf16 v[56:59], v[154:157], v[178:181], v[56:59]
	v_mfma_f32_16x16x32_bf16 v[44:47], v[146:149], v[186:189], v[44:47]
	v_mfma_f32_16x16x32_bf16 v[40:43], v[154:157], v[186:189], v[40:43]
	v_mfma_f32_16x16x32_bf16 v[28:31], v[146:149], v[194:197], v[28:31]
	v_mfma_f32_16x16x32_bf16 v[24:27], v[154:157], v[194:197], v[24:27]
	v_mfma_f32_16x16x32_bf16 v[12:15], v[146:149], v[208:211], v[12:15]
	v_mfma_f32_16x16x32_bf16 v[8:11], v[154:157], v[208:211], v[8:11]
	v_mfma_f32_16x16x32_bf16 v[60:63], v[150:153], v[182:185], v[60:63]
	v_mfma_f32_16x16x32_bf16 v[56:59], v[158:161], v[182:185], v[56:59]
	v_mfma_f32_16x16x32_bf16 v[44:47], v[150:153], v[190:193], v[44:47]
	v_mfma_f32_16x16x32_bf16 v[40:43], v[158:161], v[190:193], v[40:43]
	v_mfma_f32_16x16x32_bf16 v[28:31], v[150:153], v[198:201], v[28:31]
	v_mfma_f32_16x16x32_bf16 v[24:27], v[158:161], v[198:201], v[24:27]
	v_mfma_f32_16x16x32_bf16 v[12:15], v[150:153], v[212:215], v[12:15]
	v_mfma_f32_16x16x32_bf16 v[8:11], v[158:161], v[212:215], v[8:11]
	s_setprio 0
	s_setprio 1
	v_mfma_f32_16x16x32_bf16 v[52:55], v[162:165], v[178:181], v[52:55]
	v_mfma_f32_16x16x32_bf16 v[48:51], v[170:173], v[178:181], v[48:51]
	v_mfma_f32_16x16x32_bf16 v[36:39], v[162:165], v[186:189], v[36:39]
	v_mfma_f32_16x16x32_bf16 v[32:35], v[170:173], v[186:189], v[32:35]
	v_mfma_f32_16x16x32_bf16 v[20:23], v[162:165], v[194:197], v[20:23]
	v_mfma_f32_16x16x32_bf16 v[16:19], v[170:173], v[194:197], v[16:19]
	v_mfma_f32_16x16x32_bf16 v[4:7], v[162:165], v[208:211], v[4:7]
	v_mfma_f32_16x16x32_bf16 v[0:3], v[170:173], v[208:211], v[0:3]
	v_mfma_f32_16x16x32_bf16 v[52:55], v[166:169], v[182:185], v[52:55]
	v_mfma_f32_16x16x32_bf16 v[48:51], v[174:177], v[182:185], v[48:51]
	v_mfma_f32_16x16x32_bf16 v[36:39], v[166:169], v[190:193], v[36:39]
	v_mfma_f32_16x16x32_bf16 v[32:35], v[174:177], v[190:193], v[32:35]
	v_mfma_f32_16x16x32_bf16 v[20:23], v[166:169], v[198:201], v[20:23]
	v_mfma_f32_16x16x32_bf16 v[16:19], v[174:177], v[198:201], v[16:19]
	v_mfma_f32_16x16x32_bf16 v[4:7], v[166:169], v[212:215], v[4:7]
	v_mfma_f32_16x16x32_bf16 v[0:3], v[174:177], v[212:215], v[0:3]
	s_setprio 0
	s_barrier
	ds_read_b128 v[146:149], v144
	ds_read_b128 v[150:153], v144 offset:1024
	ds_read_b128 v[154:157], v144 offset:2048
	ds_read_b128 v[158:161], v144 offset:3072
	ds_read_b128 v[162:165], v145
	ds_read_b128 v[166:169], v145 offset:1024
	ds_read_b128 v[170:173], v145 offset:2048
	ds_read_b128 v[174:177], v145 offset:3072
	s_add_u32 s38, s38, 0x2b4000
	s_addc_u32 s39, s39, 0
	s_mov_b32 m0, s22
	v_lshl_add_u64 v[222:223], s[38:39], 0, v[128:129]
	ds_read_b128 v[178:181], v143 offset:32768
	ds_read_b128 v[182:185], v143 offset:33792
	ds_read_b128 v[186:189], v143 offset:34816
	ds_read_b128 v[190:193], v143 offset:35840
	ds_read_b128 v[194:197], v143 offset:36864
	ds_read_b128 v[198:201], v143 offset:37888
	ds_read_b128 v[208:211], v143 offset:38912
	ds_read_b128 v[212:215], v143 offset:39936
	global_load_lds_dwordx4 v[222:223], off
	v_lshl_add_u64 v[222:223], s[38:39], 0, v[132:133]
	s_mov_b32 m0, s23
	s_nop 0
	global_load_lds_dwordx4 v[222:223], off
	s_waitcnt vmcnt(8)
	s_waitcnt lgkmcnt(0)
	s_barrier
	s_setprio 1
	v_mfma_f32_16x16x32_bf16 v[124:127], v[146:149], v[178:181], v[124:127]
	v_mfma_f32_16x16x32_bf16 v[120:123], v[154:157], v[178:181], v[120:123]
	v_mfma_f32_16x16x32_bf16 v[108:111], v[146:149], v[186:189], v[108:111]
	v_mfma_f32_16x16x32_bf16 v[104:107], v[154:157], v[186:189], v[104:107]
	v_mfma_f32_16x16x32_bf16 v[92:95], v[146:149], v[194:197], v[92:95]
	v_mfma_f32_16x16x32_bf16 v[88:91], v[154:157], v[194:197], v[88:91]
	v_mfma_f32_16x16x32_bf16 v[76:79], v[146:149], v[208:211], v[76:79]
	v_mfma_f32_16x16x32_bf16 v[72:75], v[154:157], v[208:211], v[72:75]
	v_mfma_f32_16x16x32_bf16 v[124:127], v[150:153], v[182:185], v[124:127]
	v_mfma_f32_16x16x32_bf16 v[120:123], v[158:161], v[182:185], v[120:123]
	v_mfma_f32_16x16x32_bf16 v[108:111], v[150:153], v[190:193], v[108:111]
	v_mfma_f32_16x16x32_bf16 v[104:107], v[158:161], v[190:193], v[104:107]
	v_mfma_f32_16x16x32_bf16 v[92:95], v[150:153], v[198:201], v[92:95]
	v_mfma_f32_16x16x32_bf16 v[88:91], v[158:161], v[198:201], v[88:91]
	v_mfma_f32_16x16x32_bf16 v[76:79], v[150:153], v[212:215], v[76:79]
	v_mfma_f32_16x16x32_bf16 v[72:75], v[158:161], v[212:215], v[72:75]
	s_setprio 0
	s_setprio 1
	v_mfma_f32_16x16x32_bf16 v[116:119], v[162:165], v[178:181], v[116:119]
	v_mfma_f32_16x16x32_bf16 v[112:115], v[170:173], v[178:181], v[112:115]
	v_mfma_f32_16x16x32_bf16 v[100:103], v[162:165], v[186:189], v[100:103]
	v_mfma_f32_16x16x32_bf16 v[96:99], v[170:173], v[186:189], v[96:99]
	v_mfma_f32_16x16x32_bf16 v[84:87], v[162:165], v[194:197], v[84:87]
	v_mfma_f32_16x16x32_bf16 v[80:83], v[170:173], v[194:197], v[80:83]
	v_mfma_f32_16x16x32_bf16 v[68:71], v[162:165], v[208:211], v[68:71]
	v_mfma_f32_16x16x32_bf16 v[64:67], v[170:173], v[208:211], v[64:67]
	v_mfma_f32_16x16x32_bf16 v[116:119], v[166:169], v[182:185], v[116:119]
	v_mfma_f32_16x16x32_bf16 v[112:115], v[174:177], v[182:185], v[112:115]
	v_mfma_f32_16x16x32_bf16 v[100:103], v[166:169], v[190:193], v[100:103]
	v_mfma_f32_16x16x32_bf16 v[96:99], v[174:177], v[190:193], v[96:99]
	v_mfma_f32_16x16x32_bf16 v[84:87], v[166:169], v[198:201], v[84:87]
	v_mfma_f32_16x16x32_bf16 v[80:83], v[174:177], v[198:201], v[80:83]
	v_mfma_f32_16x16x32_bf16 v[68:71], v[166:169], v[212:215], v[68:71]
	v_mfma_f32_16x16x32_bf16 v[64:67], v[174:177], v[212:215], v[64:67]
	s_setprio 0
	s_barrier
; #define PG8_STAGE(bufoff, gbase, voff) do { _Pragma("unroll") for (int _i = 0; _i < 2; ++_i) \
;         __builtin_amdgcn_global_load_lds((const unsigned*)((const char*)(gbase) + (voff)[_i]), (PG8_LAS unsigned*)(lds + (bufoff) + ldsw + _i * 8192), 16, 0, 0); } while (0)
; #define PG8_STAGE_NT(bufoff, gbase, voff) do { _Pragma("unroll") for (int _i = 0; _i < 2; ++_i) \
;         __builtin_amdgcn_global_load_lds((const unsigned*)((const char*)(gbase) + (voff)[_i]), (PG8_LAS unsigned*)(lds + (bufoff) + ldsw + _i * 8192), 16, 0, PG8_B_AUX); } while (0)
; #define PG8_LDA(dst, b, h) do { _Pragma("unroll") for (int m = 0; m < 4; ++m) _Pragma("unroll") for (int k = 0; k < 2; ++k) dst[m][k] = *(const PG8_LAS bf16x8*)(lds + PG8_SA(b, h) + aoff + m * 2048 + k * 1024); } while (0)
; #define PG8_MMA(ai, bj, At, Bt) do { __builtin_amdgcn_s_setprio(1); _Pragma("unroll") for (int m = 0; m < 4; ++m) _Pragma("unroll") for (int n = 0; n < 2; ++n) _Pragma("unroll") for (int k = 0; k < 2; ++k) \
;         acc[ai][bj][m][n] = __builtin_amdgcn_mfma_f32_16x16x32_bf16(Bt[n][k], At[m][k], acc[ai][bj][m][n], 0, 0, 0); __builtin_amdgcn_s_setprio(0); } while (0)
; #define PG8_WAIT_V(n) asm volatile("s_waitcnt vmcnt(" #n ")" ::: "memory")
; #define PG8_WAIT_L(n) asm volatile("s_waitcnt lgkmcnt(" #n ")" ::: "memory")
; #define PG8_BAR __builtin_amdgcn_s_barrier()
; #define PG8_SCHED __builtin_amdgcn_sched_barrier(0)
; template <class Epi, class Sched, bool ALIGN_EPI = false, bool SP2 = false>
; __device__ __forceinline__ void gemm_phase(PG8_LAS unsigned char* lds, const Gemm g, const Sched& S, const Epi& E, int wid) {
;     ...
;             PG8_LDA(At, 1, 1); PG8_STAGE_NT(PG8_SB(1, 0), b3, voffB); PG8_STAGE_NT(PG8_SB(1, 1), b3 + hstepB, voffB); PG8_STAGE(PG8_SA(1, 0), a3, voffA);
;             PG8_WAIT_V(8); PG8_WAIT_L(0); PG8_BAR; PG8_MMA(1, 0, At, B0); PG8_MMA(1, 1, At, B1); PG8_BAR; PG8_SCHED;
;     ...
;     PG8_WAIT_V(0);
;     if constexpr (!ALIGN_EPI) { if (wr == 0) PG8_BAR; }
	s_mov_b32 m0, s63
	v_lshl_add_u64 v[202:203], v[202:203], 0, s[4:5]
	s_add_u32 s30, s30, 0x2b4080
	ds_read_b128 v[178:181], v143 offset:49152
	ds_read_b128 v[182:185], v143 offset:50176
	ds_read_b128 v[186:189], v143 offset:51200
	ds_read_b128 v[190:193], v143 offset:52224
	ds_read_b128 v[194:197], v143 offset:53248
	ds_read_b128 v[198:201], v143 offset:54272
	ds_read_b128 v[208:211], v143 offset:55296
	ds_read_b128 v[212:215], v143 offset:56320
	global_load_lds_dwordx4 v[202:203], off
	v_lshl_add_u64 v[202:203], v[216:217], 0, s[4:5]
	s_mov_b32 m0, s64
	s_addc_u32 s31, s31, 0
	global_load_lds_dwordx4 v[202:203], off
	v_lshl_add_u64 v[202:203], s[30:31], 0, v[130:131]
	s_mov_b32 m0, s65
	s_nop 0
	global_load_lds_dwordx4 v[202:203], off
	v_lshl_add_u64 v[202:203], s[30:31], 0, v[134:135]
	s_mov_b32 m0, s66
	s_nop 0
	global_load_lds_dwordx4 v[202:203], off
	v_lshl_add_u64 v[202:203], v[218:219], 0, s[4:5]
	s_mov_b32 m0, s25
	s_nop 0
	global_load_lds_dwordx4 v[202:203], off
	v_lshl_add_u64 v[202:203], v[220:221], 0, s[4:5]
	s_mov_b32 m0, s56
	s_nop 0
	global_load_lds_dwordx4 v[202:203], off
	s_nop 0
	s_waitcnt vmcnt(8)
	s_waitcnt lgkmcnt(0)
	s_barrier
	s_setprio 1
	v_mfma_f32_16x16x32_bf16 v[60:63], v[146:149], v[178:181], v[60:63]
	v_mfma_f32_16x16x32_bf16 v[56:59], v[154:157], v[178:181], v[56:59]
	v_mfma_f32_16x16x32_bf16 v[44:47], v[146:149], v[186:189], v[44:47]
	v_mfma_f32_16x16x32_bf16 v[40:43], v[154:157], v[186:189], v[40:43]
	v_mfma_f32_16x16x32_bf16 v[28:31], v[146:149], v[194:197], v[28:31]
	v_mfma_f32_16x16x32_bf16 v[24:27], v[154:157], v[194:197], v[24:27]
	v_mfma_f32_16x16x32_bf16 v[12:15], v[146:149], v[208:211], v[12:15]
	v_mfma_f32_16x16x32_bf16 v[8:11], v[154:157], v[208:211], v[8:11]
	v_mfma_f32_16x16x32_bf16 v[60:63], v[150:153], v[182:185], v[60:63]
	v_mfma_f32_16x16x32_bf16 v[56:59], v[158:161], v[182:185], v[56:59]
	v_mfma_f32_16x16x32_bf16 v[44:47], v[150:153], v[190:193], v[44:47]
	v_mfma_f32_16x16x32_bf16 v[40:43], v[158:161], v[190:193], v[40:43]
	v_mfma_f32_16x16x32_bf16 v[28:31], v[150:153], v[198:201], v[28:31]
	v_mfma_f32_16x16x32_bf16 v[24:27], v[158:161], v[198:201], v[24:27]
	v_mfma_f32_16x16x32_bf16 v[12:15], v[150:153], v[212:215], v[12:15]
	v_mfma_f32_16x16x32_bf16 v[8:11], v[158:161], v[212:215], v[8:11]
	s_setprio 0
	s_setprio 1
	v_mfma_f32_16x16x32_bf16 v[52:55], v[162:165], v[178:181], v[52:55]
	v_mfma_f32_16x16x32_bf16 v[48:51], v[170:173], v[178:181], v[48:51]
	v_mfma_f32_16x16x32_bf16 v[36:39], v[162:165], v[186:189], v[36:39]
	v_mfma_f32_16x16x32_bf16 v[32:35], v[170:173], v[186:189], v[32:35]
	v_mfma_f32_16x16x32_bf16 v[20:23], v[162:165], v[194:197], v[20:23]
	v_mfma_f32_16x16x32_bf16 v[16:19], v[170:173], v[194:197], v[16:19]
	v_mfma_f32_16x16x32_bf16 v[4:7], v[162:165], v[208:211], v[4:7]
	v_mfma_f32_16x16x32_bf16 v[0:3], v[170:173], v[208:211], v[0:3]
	v_mfma_f32_16x16x32_bf16 v[52:55], v[166:169], v[182:185], v[52:55]
	v_mfma_f32_16x16x32_bf16 v[48:51], v[174:177], v[182:185], v[48:51]
	v_mfma_f32_16x16x32_bf16 v[36:39], v[166:169], v[190:193], v[36:39]
	v_mfma_f32_16x16x32_bf16 v[32:35], v[174:177], v[190:193], v[32:35]
	v_mfma_f32_16x16x32_bf16 v[20:23], v[166:169], v[198:201], v[20:23]
	v_mfma_f32_16x16x32_bf16 v[16:19], v[174:177], v[198:201], v[16:19]
	v_mfma_f32_16x16x32_bf16 v[4:7], v[166:169], v[212:215], v[4:7]
	v_mfma_f32_16x16x32_bf16 v[0:3], v[174:177], v[212:215], v[0:3]
	s_setprio 0
	s_barrier
	s_add_i32 s41, s41, 2
	s_add_u32 s21, s21, 0x100
	s_addc_u32 s40, s40, 0
	s_add_u32 s8, s8, 0x100
	s_addc_u32 s9, s9, 0
	v_lshl_add_u64 v[136:137], v[136:137], 0, s[28:29]
	s_cmpk_lt_u32 s41, 0xaa
	v_lshl_add_u64 v[138:139], v[138:139], 0, s[28:29]
	s_cbranch_scc1 .LBB0_1307
	s_waitcnt vmcnt(0)
	s_andn2_b64 vcc, exec, s[44:45]
	s_cbranch_vccnz .LBB0_1310
	s_barrier
